# cache policy: f32 weight reads of the bf16 transposes (read once, ~200 MB) non-temporal, on top of non-temporal a2 stores
# speedup vs baseline: 1.0155x; 1.0082x over previous
; #define LAS __attribute__((address_space(3)))
; __device__ __forceinline__ void transpose_item(const float* W, int K, int N, bf16_t* WT, LAS float* scr, int item, int lane) {
;     const int nblk = N / 32, kb = item / nblk, nb = item % nblk, k0 = 64 * kb, n0 = 32 * nb;
;     float wv[32];
; #pragma unroll
;     for (int i = 0; i < 32; ++i) wv[i] = W[(size_t)(k0 + 2 * i + (lane >> 5)) * N + n0 + (lane & 31)];
; #pragma unroll
;     for (int i = 0; i < 32; ++i) scr[(2 * i + (lane >> 5)) * 33 + (lane & 31)] = wv[i];
.LBB0_1106:
	s_lshr_b32 s22, s34, 5
	v_cvt_f32_u32_e32 v1, s22
	s_sub_i32 s70, 0, s22
	s_abs_i32 s60, s61
	s_ashr_i32 s23, s61, 31
	v_rcp_iflag_f32_e32 v1, v1
	s_nop 0
	v_mul_f32_e32 v1, 0x4f7ffffe, v1
	v_cvt_u32_f32_e32 v1, v1
	s_nop 0
	v_readfirstlane_b32 s71, v1
	s_mul_i32 s70, s70, s71
	s_mul_hi_u32 s70, s71, s70
	s_add_i32 s71, s71, s70
	s_mul_hi_u32 s70, s60, s71
	s_mul_i32 s71, s70, s22
	s_sub_i32 s60, s60, s71
	s_add_i32 s71, s70, 1
	s_sub_i32 s82, s60, s22
	s_cmp_ge_u32 s60, s22
	s_cselect_b32 s70, s71, s70
	s_cselect_b32 s60, s82, s60
	s_add_i32 s71, s70, 1
	s_cmp_ge_u32 s60, s22
	s_cselect_b32 s60, s71, s70
	s_xor_b32 s60, s60, s23
	s_sub_i32 s23, s60, s23
	s_mul_i32 s22, s23, s22
	s_sub_i32 s60, s61, s22
	s_lshl_b32 s60, s60, 5
	s_ashr_i32 s61, s60, 31
	s_lshl_b32 s22, s23, 6
	s_lshl_b64 s[70:71], s[60:61], 2
	s_add_u32 s70, s78, s70
	v_or_b32_e32 v1, s22, v4
	s_addc_u32 s71, s79, s71
	s_ashr_i32 s23, s22, 31
	v_lshl_add_u64 v[2:3], s[70:71], 0, v[96:97]
	s_mul_i32 s78, s23, s34
	v_mad_u64_u32 v[12:13], s[70:71], v1, s34, 0
	v_add_u32_e32 v13, s78, v13
	v_lshl_add_u64 v[12:13], v[12:13], 2, v[2:3]
	global_load_dword v11, v[12:13], off nt
	v_or_b32_e32 v12, 2, v1
	v_mad_u64_u32 v[12:13], s[70:71], v12, s34, 0
	v_add_u32_e32 v13, s78, v13
	v_lshl_add_u64 v[12:13], v[12:13], 2, v[2:3]
	global_load_dword v14, v[12:13], off nt
	v_or_b32_e32 v12, 4, v1
	v_mad_u64_u32 v[12:13], s[70:71], v12, s34, 0
	v_add_u32_e32 v13, s78, v13
	v_lshl_add_u64 v[12:13], v[12:13], 2, v[2:3]
	global_load_dword v15, v[12:13], off nt
	v_or_b32_e32 v12, 6, v1
	v_mad_u64_u32 v[12:13], s[70:71], v12, s34, 0
	v_add_u32_e32 v13, s78, v13
	v_lshl_add_u64 v[12:13], v[12:13], 2, v[2:3]
	global_load_dword v16, v[12:13], off nt
	v_or_b32_e32 v12, 8, v1
	v_mad_u64_u32 v[12:13], s[70:71], v12, s34, 0
	v_add_u32_e32 v13, s78, v13
	v_lshl_add_u64 v[12:13], v[12:13], 2, v[2:3]
	global_load_dword v17, v[12:13], off nt
	v_or_b32_e32 v12, 10, v1
	v_mad_u64_u32 v[12:13], s[70:71], v12, s34, 0
	v_add_u32_e32 v13, s78, v13
	v_lshl_add_u64 v[12:13], v[12:13], 2, v[2:3]
	global_load_dword v18, v[12:13], off nt
	v_or_b32_e32 v12, 12, v1
	v_mad_u64_u32 v[12:13], s[70:71], v12, s34, 0
	v_add_u32_e32 v13, s78, v13
	v_lshl_add_u64 v[12:13], v[12:13], 2, v[2:3]
	global_load_dword v19, v[12:13], off nt
	v_or_b32_e32 v12, 14, v1
	v_mad_u64_u32 v[12:13], s[70:71], v12, s34, 0
	v_add_u32_e32 v13, s78, v13
	v_lshl_add_u64 v[12:13], v[12:13], 2, v[2:3]
	global_load_dword v20, v[12:13], off nt
	v_or_b32_e32 v12, 16, v1
	v_mad_u64_u32 v[12:13], s[70:71], v12, s34, 0
	v_add_u32_e32 v13, s78, v13
	v_lshl_add_u64 v[12:13], v[12:13], 2, v[2:3]
	global_load_dword v21, v[12:13], off nt
	v_or_b32_e32 v12, 18, v1
	v_mad_u64_u32 v[12:13], s[70:71], v12, s34, 0
	v_add_u32_e32 v13, s78, v13
	v_lshl_add_u64 v[12:13], v[12:13], 2, v[2:3]
	global_load_dword v22, v[12:13], off nt
	v_or_b32_e32 v12, 20, v1
	v_mad_u64_u32 v[12:13], s[70:71], v12, s34, 0
	v_add_u32_e32 v13, s78, v13
	v_lshl_add_u64 v[12:13], v[12:13], 2, v[2:3]
	global_load_dword v23, v[12:13], off nt
	v_or_b32_e32 v12, 22, v1
	v_mad_u64_u32 v[12:13], s[70:71], v12, s34, 0
	v_add_u32_e32 v13, s78, v13
	v_lshl_add_u64 v[12:13], v[12:13], 2, v[2:3]
	global_load_dword v24, v[12:13], off nt
	v_or_b32_e32 v12, 24, v1
	v_mad_u64_u32 v[12:13], s[70:71], v12, s34, 0
	v_add_u32_e32 v13, s78, v13
	v_lshl_add_u64 v[12:13], v[12:13], 2, v[2:3]
	global_load_dword v25, v[12:13], off nt
	v_or_b32_e32 v12, 26, v1
	v_mad_u64_u32 v[12:13], s[70:71], v12, s34, 0
	v_add_u32_e32 v13, s78, v13
	v_lshl_add_u64 v[12:13], v[12:13], 2, v[2:3]
	global_load_dword v26, v[12:13], off nt
	v_or_b32_e32 v12, 28, v1
	v_mad_u64_u32 v[12:13], s[70:71], v12, s34, 0
	v_add_u32_e32 v13, s78, v13
	v_lshl_add_u64 v[12:13], v[12:13], 2, v[2:3]
	global_load_dword v27, v[12:13], off nt
	v_or_b32_e32 v12, 30, v1
	v_mad_u64_u32 v[12:13], s[70:71], v12, s34, 0
	v_add_u32_e32 v13, s78, v13
	v_lshl_add_u64 v[12:13], v[12:13], 2, v[2:3]
	global_load_dword v28, v[12:13], off nt
	v_or_b32_e32 v12, 32, v1
	v_mad_u64_u32 v[12:13], s[70:71], v12, s34, 0
	v_add_u32_e32 v13, s78, v13
	v_lshl_add_u64 v[12:13], v[12:13], 2, v[2:3]
	global_load_dword v29, v[12:13], off nt
	v_or_b32_e32 v12, 34, v1
	v_mad_u64_u32 v[12:13], s[70:71], v12, s34, 0
	v_add_u32_e32 v13, s78, v13
	v_lshl_add_u64 v[12:13], v[12:13], 2, v[2:3]
	global_load_dword v30, v[12:13], off nt
	v_or_b32_e32 v12, 36, v1
	v_mad_u64_u32 v[12:13], s[70:71], v12, s34, 0
	v_add_u32_e32 v13, s78, v13
	v_lshl_add_u64 v[12:13], v[12:13], 2, v[2:3]
	global_load_dword v31, v[12:13], off nt
	v_or_b32_e32 v12, 38, v1
	v_mad_u64_u32 v[12:13], s[70:71], v12, s34, 0
	v_add_u32_e32 v13, s78, v13
	v_lshl_add_u64 v[12:13], v[12:13], 2, v[2:3]
	global_load_dword v32, v[12:13], off nt
	v_or_b32_e32 v12, 40, v1
	v_mad_u64_u32 v[12:13], s[70:71], v12, s34, 0
	v_add_u32_e32 v13, s78, v13
	v_lshl_add_u64 v[12:13], v[12:13], 2, v[2:3]
	global_load_dword v33, v[12:13], off nt
	v_or_b32_e32 v12, 42, v1
	v_mad_u64_u32 v[12:13], s[70:71], v12, s34, 0
	v_add_u32_e32 v13, s78, v13
	v_lshl_add_u64 v[12:13], v[12:13], 2, v[2:3]
	global_load_dword v34, v[12:13], off nt
	v_or_b32_e32 v12, 44, v1
	v_mad_u64_u32 v[12:13], s[70:71], v12, s34, 0
	v_add_u32_e32 v13, s78, v13
	v_lshl_add_u64 v[12:13], v[12:13], 2, v[2:3]
	global_load_dword v35, v[12:13], off nt
	v_or_b32_e32 v12, 46, v1
	v_mad_u64_u32 v[12:13], s[70:71], v12, s34, 0
	v_add_u32_e32 v13, s78, v13
	v_lshl_add_u64 v[12:13], v[12:13], 2, v[2:3]
	global_load_dword v36, v[12:13], off nt
	v_or_b32_e32 v12, 48, v1
	v_mad_u64_u32 v[12:13], s[70:71], v12, s34, 0
	v_add_u32_e32 v13, s78, v13
	v_lshl_add_u64 v[12:13], v[12:13], 2, v[2:3]
; #define LAS __attribute__((address_space(3)))
; __device__ __forceinline__ unsigned pk2(float lo, float hi) { return f2bf(lo) | (f2bf(hi) << 16); }
; __device__ __forceinline__ void transpose_item(const float* W, int K, int N, bf16_t* WT, LAS float* scr, int item, int lane) {
;     ...
;     for (int i = 0; i < 32; ++i) wv[i] = W[(size_t)(k0 + 2 * i + (lane >> 5)) * N + n0 + (lane & 31)];
; #pragma unroll
;     for (int i = 0; i < 32; ++i) scr[(2 * i + (lane >> 5)) * 33 + (lane & 31)] = wv[i];
;     asm volatile("s_waitcnt lgkmcnt(0)" ::: "memory");
;     const int c = lane & 7;
; #pragma unroll
;     for (int j = 0; j < 4; ++j) { const int n = (lane >> 3) + 8 * j; const LAS float* s = scr + (8 * c) * 33 + n;
;         u32x4 o; o.x = pk2(s[0 * 33], s[1 * 33]); o.y = pk2(s[2 * 33], s[3 * 33]); o.z = pk2(s[4 * 33], s[5 * 33]); o.w = pk2(s[6 * 33], s[7 * 33]);
;         *(u32x4*)(WT + (size_t)(n0 + n) * K + k0 + 8 * c) = o; }
	global_load_dword v37, v[12:13], off nt
	v_or_b32_e32 v12, 50, v1
	v_mad_u64_u32 v[12:13], s[70:71], v12, s34, 0
	v_add_u32_e32 v13, s78, v13
	v_lshl_add_u64 v[12:13], v[12:13], 2, v[2:3]
	global_load_dword v38, v[12:13], off nt
	v_or_b32_e32 v12, 52, v1
	v_mad_u64_u32 v[12:13], s[70:71], v12, s34, 0
	v_add_u32_e32 v13, s78, v13
	v_lshl_add_u64 v[12:13], v[12:13], 2, v[2:3]
	global_load_dword v39, v[12:13], off nt
	v_or_b32_e32 v12, 54, v1
	v_mad_u64_u32 v[12:13], s[70:71], v12, s34, 0
	v_add_u32_e32 v13, s78, v13
	v_lshl_add_u64 v[12:13], v[12:13], 2, v[2:3]
	global_load_dword v40, v[12:13], off nt
	v_or_b32_e32 v12, 56, v1
	v_mad_u64_u32 v[12:13], s[70:71], v12, s34, 0
	v_add_u32_e32 v13, s78, v13
	v_lshl_add_u64 v[12:13], v[12:13], 2, v[2:3]
	global_load_dword v41, v[12:13], off nt
	v_or_b32_e32 v12, 58, v1
	v_mad_u64_u32 v[12:13], s[70:71], v12, s34, 0
	v_add_u32_e32 v13, s78, v13
	v_lshl_add_u64 v[12:13], v[12:13], 2, v[2:3]
	global_load_dword v42, v[12:13], off nt
	v_or_b32_e32 v12, 60, v1
	v_mad_u64_u32 v[12:13], s[70:71], v12, s34, 0
	v_add_u32_e32 v13, s78, v13
	v_lshl_add_u64 v[12:13], v[12:13], 2, v[2:3]
	v_or_b32_e32 v1, 62, v1
	global_load_dword v43, v[12:13], off nt
	v_mad_u64_u32 v[12:13], s[70:71], v1, s34, 0
	v_add_u32_e32 v13, s78, v13
	v_lshl_add_u64 v[2:3], v[12:13], 2, v[2:3]
	global_load_dword v1, v[2:3], off nt
	v_add_u32_e32 v2, 0x400, v10
	s_waitcnt vmcnt(0)
	ds_write2_b32 v10, v11, v14 offset1:66
	ds_write2_b32 v10, v15, v16 offset0:132 offset1:198
	ds_write2_b32 v2, v17, v18 offset0:8 offset1:74
	ds_write2_b32 v2, v19, v20 offset0:140 offset1:206
	v_add_u32_e32 v2, 0x800, v10
	ds_write2_b32 v2, v21, v22 offset0:16 offset1:82
	ds_write2_b32 v2, v23, v24 offset0:148 offset1:214
	v_add_u32_e32 v2, 0xc00, v10
	ds_write2_b32 v2, v25, v26 offset0:24 offset1:90
	ds_write2_b32 v2, v27, v28 offset0:156 offset1:222
	v_add_u32_e32 v2, 0x1000, v10
	ds_write2_b32 v2, v29, v30 offset0:32 offset1:98
	ds_write2_b32 v2, v31, v32 offset0:164 offset1:230
	v_add_u32_e32 v2, 0x1400, v10
	ds_write2_b32 v2, v33, v34 offset0:40 offset1:106
	ds_write2_b32 v2, v35, v36 offset0:172 offset1:238
	v_add_u32_e32 v2, 0x1800, v10
	ds_write2_b32 v2, v37, v38 offset0:48 offset1:114
	ds_write2_b32 v2, v39, v40 offset0:180 offset1:246
	v_add_u32_e32 v2, 0x1c00, v10
	ds_write2_b32 v2, v41, v42 offset0:56 offset1:122
	ds_write2_b32 v2, v43, v1 offset0:188 offset1:254
	s_waitcnt lgkmcnt(0)
	ds_read2_b32 v[16:17], v6 offset0:33 offset1:41
	ds_read2_b32 v[18:19], v6 offset1:8
	s_lshl_b64 s[22:23], s[22:23], 1
	s_add_u32 s22, s76, s22
	s_addc_u32 s23, s77, s23
	v_mov_b32_e32 v1, v97
	ds_read2_b32 v[20:21], v6 offset0:66 offset1:74
	ds_read2_b32 v[22:23], v6 offset0:99 offset1:107
	v_lshl_add_u64 v[2:3], s[22:23], 0, v[0:1]
	s_waitcnt lgkmcnt(2)
	v_bfe_u32 v1, v18, 16, 1
	v_add3_u32 v1, v18, v1, s28
	v_bfe_u32 v11, v16, 16, 1
	v_lshrrev_b32_e32 v1, 16, v1
	v_add3_u32 v11, v16, v11, s28
	ds_read2_b32 v[24:25], v6 offset0:132 offset1:140
	ds_read2_b32 v[26:27], v6 offset0:165 offset1:173
	v_and_or_b32 v12, v11, s39, v1
	s_waitcnt lgkmcnt(3)
	v_bfe_u32 v1, v20, 16, 1
	v_add3_u32 v1, v20, v1, s28
	s_waitcnt lgkmcnt(2)
	v_bfe_u32 v11, v22, 16, 1
	v_lshrrev_b32_e32 v1, 16, v1
	v_add3_u32 v11, v22, v11, s28
	ds_read2_b32 v[28:29], v6 offset0:198 offset1:206
	ds_read2_b32 v[30:31], v6 offset0:231 offset1:239
	v_and_or_b32 v13, v11, s39, v1
	s_waitcnt lgkmcnt(3)
	v_bfe_u32 v1, v24, 16, 1
	v_add3_u32 v1, v24, v1, s28
	s_waitcnt lgkmcnt(2)
	v_bfe_u32 v11, v26, 16, 1
	v_lshrrev_b32_e32 v1, 16, v1
	v_add3_u32 v11, v26, v11, s28
	v_and_or_b32 v14, v11, s39, v1
	s_waitcnt lgkmcnt(1)
	v_bfe_u32 v1, v28, 16, 1
	v_add3_u32 v1, v28, v1, s28
	s_waitcnt lgkmcnt(0)
; #define LAS __attribute__((address_space(3)))
; __device__ __forceinline__ unsigned pk2(float lo, float hi) { return f2bf(lo) | (f2bf(hi) << 16); }
; __device__ __forceinline__ void transpose_item(const float* W, int K, int N, bf16_t* WT, LAS float* scr, int item, int lane) {
;     ...
;     const int c = lane & 7;
; #pragma unroll
;     for (int j = 0; j < 4; ++j) { const int n = (lane >> 3) + 8 * j; const LAS float* s = scr + (8 * c) * 33 + n;
;         u32x4 o; o.x = pk2(s[0 * 33], s[1 * 33]); o.y = pk2(s[2 * 33], s[3 * 33]); o.z = pk2(s[4 * 33], s[5 * 33]); o.w = pk2(s[6 * 33], s[7 * 33]);
;         *(u32x4*)(WT + (size_t)(n0 + n) * K + k0 + 8 * c) = o; }
;     asm volatile("s_waitcnt lgkmcnt(0)" ::: "memory");
	v_bfe_u32 v11, v30, 16, 1
	v_lshrrev_b32_e32 v1, 16, v1
	v_add3_u32 v11, v30, v11, s28
	v_and_or_b32 v15, v11, s39, v1
	v_or_b32_e32 v1, s60, v5
	v_mad_u64_u32 v[32:33], s[22:23], s58, v1, 0
	v_mul_lo_u32 v11, s59, v1
	s_mul_i32 s22, s58, s61
	v_bfe_u32 v1, v19, 16, 1
	v_add3_u32 v33, v33, s22, v11
	v_add3_u32 v1, v19, v1, s28
	v_bfe_u32 v11, v17, 16, 1
	v_lshl_add_u64 v[32:33], v[32:33], 1, v[2:3]
	v_lshrrev_b32_e32 v1, 16, v1
	v_add3_u32 v11, v17, v11, s28
	global_store_dwordx4 v[32:33], v[12:15], off
	s_add_i32 s81, s81, s73
	s_add_i32 s69, s69, s73
	v_and_or_b32 v12, v11, s39, v1
	v_bfe_u32 v1, v21, 16, 1
	v_add3_u32 v1, v21, v1, s28
	v_bfe_u32 v11, v23, 16, 1
	v_lshrrev_b32_e32 v1, 16, v1
	v_add3_u32 v11, v23, v11, s28
	v_and_or_b32 v13, v11, s39, v1
	v_bfe_u32 v1, v25, 16, 1
	v_add3_u32 v1, v25, v1, s28
	v_bfe_u32 v11, v27, 16, 1
	v_lshrrev_b32_e32 v1, 16, v1
	v_add3_u32 v11, v27, v11, s28
	v_and_or_b32 v14, v11, s39, v1
	v_bfe_u32 v1, v29, 16, 1
	v_add3_u32 v1, v29, v1, s28
	v_bfe_u32 v11, v31, 16, 1
	v_lshrrev_b32_e32 v1, 16, v1
	v_add3_u32 v11, v31, v11, s28
	v_and_or_b32 v15, v11, s39, v1
	v_or_b32_e32 v1, s60, v7
	v_mul_lo_u32 v11, s59, v1
	v_mad_u64_u32 v[16:17], s[70:71], s58, v1, 0
	v_add3_u32 v17, v17, s22, v11
	v_lshl_add_u64 v[16:17], v[16:17], 1, v[2:3]
	global_store_dwordx4 v[16:17], v[12:15], off
	ds_read2_b32 v[16:17], v6 offset0:16 offset1:24
	ds_read2_b32 v[18:19], v6 offset0:49 offset1:57
	ds_read2_b32 v[20:21], v6 offset0:82 offset1:90
	ds_read2_b32 v[22:23], v6 offset0:115 offset1:123
	ds_read2_b32 v[24:25], v6 offset0:148 offset1:156
	ds_read2_b32 v[26:27], v6 offset0:181 offset1:189
	ds_read2_b32 v[28:29], v6 offset0:214 offset1:222
	ds_read2_b32 v[30:31], v6 offset0:247 offset1:255
	s_waitcnt lgkmcnt(7)
	v_bfe_u32 v1, v16, 16, 1
	v_add3_u32 v1, v16, v1, s28
	s_waitcnt lgkmcnt(6)
	v_bfe_u32 v11, v18, 16, 1
	v_lshrrev_b32_e32 v1, 16, v1
	v_add3_u32 v11, v18, v11, s28
	v_and_or_b32 v12, v11, s39, v1
	s_waitcnt lgkmcnt(5)
	v_bfe_u32 v1, v20, 16, 1
	v_add3_u32 v1, v20, v1, s28
	s_waitcnt lgkmcnt(4)
	v_bfe_u32 v11, v22, 16, 1
	v_lshrrev_b32_e32 v1, 16, v1
	v_add3_u32 v11, v22, v11, s28
	v_and_or_b32 v13, v11, s39, v1
	s_waitcnt lgkmcnt(3)
	v_bfe_u32 v1, v24, 16, 1
	v_add3_u32 v1, v24, v1, s28
	s_waitcnt lgkmcnt(2)
	v_bfe_u32 v11, v26, 16, 1
	v_lshrrev_b32_e32 v1, 16, v1
	v_add3_u32 v11, v26, v11, s28
	v_and_or_b32 v14, v11, s39, v1
	s_waitcnt lgkmcnt(1)
	v_bfe_u32 v1, v28, 16, 1
	v_add3_u32 v1, v28, v1, s28
	s_waitcnt lgkmcnt(0)
	v_bfe_u32 v11, v30, 16, 1
	v_lshrrev_b32_e32 v1, 16, v1
	v_add3_u32 v11, v30, v11, s28
	v_and_or_b32 v15, v11, s39, v1
	v_or_b32_e32 v1, s60, v8
	v_mul_lo_u32 v11, s59, v1
	v_mad_u64_u32 v[32:33], s[70:71], s58, v1, 0
	v_bfe_u32 v1, v17, 16, 1
	v_add3_u32 v33, v33, s22, v11
	v_add3_u32 v1, v17, v1, s28
	v_bfe_u32 v11, v19, 16, 1
	v_lshl_add_u64 v[32:33], v[32:33], 1, v[2:3]
	v_lshrrev_b32_e32 v1, 16, v1
	v_add3_u32 v11, v19, v11, s28
	global_store_dwordx4 v[32:33], v[12:15], off
	s_add_i32 s74, s74, s73
	s_add_i32 s75, s75, s73
	v_and_or_b32 v12, v11, s39, v1
	v_bfe_u32 v1, v21, 16, 1
	v_add3_u32 v1, v21, v1, s28
	v_bfe_u32 v11, v23, 16, 1
	v_lshrrev_b32_e32 v1, 16, v1
	v_add3_u32 v11, v23, v11, s28
	v_and_or_b32 v13, v11, s39, v1
	v_bfe_u32 v1, v25, 16, 1
	v_add3_u32 v1, v25, v1, s28
	v_bfe_u32 v11, v27, 16, 1
	v_lshrrev_b32_e32 v1, 16, v1
	v_add3_u32 v11, v27, v11, s28
	v_and_or_b32 v14, v11, s39, v1
	v_bfe_u32 v1, v29, 16, 1
	v_add3_u32 v1, v29, v1, s28
	v_bfe_u32 v11, v31, 16, 1
	v_lshrrev_b32_e32 v1, 16, v1
	v_add3_u32 v11, v31, v11, s28
	v_and_or_b32 v15, v11, s39, v1
	v_or_b32_e32 v1, s60, v9
	v_mul_lo_u32 v11, s59, v1
	v_mad_u64_u32 v[16:17], s[58:59], s58, v1, 0
	v_add3_u32 v17, v17, s22, v11
	v_lshl_add_u64 v[2:3], v[16:17], 1, v[2:3]
	global_store_dwordx4 v[2:3], v[12:15], off
	s_waitcnt lgkmcnt(0)
	s_sub_i32 s22, s37, s44
	s_add_i32 s37, s22, 0x800
	s_add_i32 s80, s80, s73
	s_add_i32 s22, s89, s81
	s_cmp_ge_i32 s22, s38
	s_movk_i32 s82, 0x2000
	s_cbranch_scc1 .LBB0_1154

; #define LAS __attribute__((address_space(3)))
; __device__ __forceinline__ void transpose_item(const float* W, int K, int N, bf16_t* WT, LAS float* scr, int item, int lane) {
;     const int nblk = N / 32, kb = item / nblk, nb = item % nblk, k0 = 64 * kb, n0 = 32 * nb;
;     float wv[32];
; #pragma unroll
;     for (int i = 0; i < 32; ++i) wv[i] = W[(size_t)(k0 + 2 * i + (lane >> 5)) * N + n0 + (lane & 31)];
; #pragma unroll
;     for (int i = 0; i < 32; ++i) scr[(2 * i + (lane >> 5)) * 33 + (lane & 31)] = wv[i];
.LBB0_1170:
	s_lshr_b32 s22, s34, 5
	v_cvt_f32_u32_e32 v1, s22
	s_sub_i32 s44, 0, s22
	s_abs_i32 s37, s38
	s_ashr_i32 s23, s38, 31
	v_rcp_iflag_f32_e32 v1, v1
	s_nop 0
	v_mul_f32_e32 v1, 0x4f7ffffe, v1
	v_cvt_u32_f32_e32 v1, v1
	s_nop 0
	v_readfirstlane_b32 s45, v1
	s_mul_i32 s44, s44, s45
	s_mul_hi_u32 s44, s45, s44
	s_add_i32 s45, s45, s44
	s_mul_hi_u32 s44, s37, s45
	s_mul_i32 s45, s44, s22
	s_sub_i32 s37, s37, s45
	s_add_i32 s46, s44, 1
	s_sub_i32 s45, s37, s22
	s_cmp_ge_u32 s37, s22
	s_cselect_b32 s44, s46, s44
	s_cselect_b32 s37, s45, s37
	s_add_i32 s45, s44, 1
	s_cmp_ge_u32 s37, s22
	s_cselect_b32 s37, s45, s44
	s_xor_b32 s37, s37, s23
	s_sub_i32 s23, s37, s23
	s_mul_i32 s22, s23, s22
	s_sub_i32 s22, s38, s22
	s_lshl_b32 s22, s22, 5
	s_lshl_b32 s72, s23, 6
	s_ashr_i32 s23, s22, 31
	s_lshl_b64 s[44:45], s[22:23], 2
	v_or_b32_e32 v1, s72, v2
	s_waitcnt lgkmcnt(0)
	s_add_u32 s44, s70, s44
	s_addc_u32 s45, s71, s45
	v_or_b32_e32 v11, 2, v1
	v_lshl_add_u64 v[12:13], s[44:45], 0, v[96:97]
	v_mad_u64_u32 v[16:17], s[44:45], v11, s34, 0
	v_or_b32_e32 v11, 4, v1
	v_mad_u64_u32 v[18:19], s[44:45], v11, s34, 0
	v_or_b32_e32 v11, 6, v1
	v_mad_u64_u32 v[20:21], s[44:45], v11, s34, 0
	v_or_b32_e32 v11, 8, v1
	v_mad_u64_u32 v[22:23], s[44:45], v11, s34, 0
	v_or_b32_e32 v11, 10, v1
	s_ashr_i32 s73, s72, 31
	v_mad_u64_u32 v[24:25], s[44:45], v11, s34, 0
	v_or_b32_e32 v11, 12, v1
	s_mul_i32 s37, s73, s34
	v_mad_u64_u32 v[14:15], s[44:45], v1, s34, 0
	v_mad_u64_u32 v[26:27], s[44:45], v11, s34, 0
	v_or_b32_e32 v11, 14, v1
	v_add_u32_e32 v15, s37, v15
	v_add_u32_e32 v17, s37, v17
	v_add_u32_e32 v19, s37, v19
	v_add_u32_e32 v21, s37, v21
	v_add_u32_e32 v23, s37, v23
	v_add_u32_e32 v25, s37, v25
	v_add_u32_e32 v27, s37, v27
	s_waitcnt vmcnt(0)
	v_mad_u64_u32 v[28:29], s[44:45], v11, s34, 0
	v_lshl_add_u64 v[14:15], v[14:15], 2, v[12:13]
	v_lshl_add_u64 v[16:17], v[16:17], 2, v[12:13]
	v_lshl_add_u64 v[18:19], v[18:19], 2, v[12:13]
	v_lshl_add_u64 v[20:21], v[20:21], 2, v[12:13]
	v_lshl_add_u64 v[22:23], v[22:23], 2, v[12:13]
	v_lshl_add_u64 v[24:25], v[24:25], 2, v[12:13]
	v_lshl_add_u64 v[26:27], v[26:27], 2, v[12:13]
	v_add_u32_e32 v29, s37, v29
	v_lshl_add_u64 v[28:29], v[28:29], 2, v[12:13]
	global_load_dword v11, v[14:15], off nt
	global_load_dword v30, v[16:17], off nt
	global_load_dword v31, v[18:19], off nt
	global_load_dword v32, v[20:21], off nt
	global_load_dword v33, v[22:23], off nt
	global_load_dword v34, v[24:25], off nt
	global_load_dword v35, v[26:27], off nt
	global_load_dword v36, v[28:29], off nt
	v_or_b32_e32 v14, 16, v1
	v_or_b32_e32 v16, 18, v1
	v_or_b32_e32 v18, 20, v1
	v_or_b32_e32 v20, 22, v1
	v_or_b32_e32 v22, 24, v1
	v_or_b32_e32 v24, 26, v1
	v_or_b32_e32 v26, 28, v1
	v_mad_u64_u32 v[14:15], s[44:45], v14, s34, 0
	v_mad_u64_u32 v[16:17], s[44:45], v16, s34, 0
	v_mad_u64_u32 v[18:19], s[44:45], v18, s34, 0
	v_mad_u64_u32 v[20:21], s[44:45], v20, s34, 0
	v_mad_u64_u32 v[22:23], s[44:45], v22, s34, 0
	v_mad_u64_u32 v[24:25], s[44:45], v24, s34, 0
	v_mad_u64_u32 v[26:27], s[44:45], v26, s34, 0
	v_or_b32_e32 v28, 30, v1
	v_add_u32_e32 v15, s37, v15
	v_add_u32_e32 v17, s37, v17
	v_add_u32_e32 v19, s37, v19
	v_add_u32_e32 v21, s37, v21
	v_add_u32_e32 v23, s37, v23
	v_add_u32_e32 v25, s37, v25
	v_add_u32_e32 v27, s37, v27
	v_mad_u64_u32 v[28:29], s[44:45], v28, s34, 0
	v_lshl_add_u64 v[14:15], v[14:15], 2, v[12:13]
	v_lshl_add_u64 v[16:17], v[16:17], 2, v[12:13]
	v_lshl_add_u64 v[18:19], v[18:19], 2, v[12:13]
	v_lshl_add_u64 v[20:21], v[20:21], 2, v[12:13]
	v_lshl_add_u64 v[22:23], v[22:23], 2, v[12:13]
	v_lshl_add_u64 v[24:25], v[24:25], 2, v[12:13]
	v_lshl_add_u64 v[26:27], v[26:27], 2, v[12:13]
	v_add_u32_e32 v29, s37, v29
	v_lshl_add_u64 v[28:29], v[28:29], 2, v[12:13]
	global_load_dword v37, v[14:15], off nt
	global_load_dword v38, v[16:17], off nt
	global_load_dword v39, v[18:19], off nt
	global_load_dword v40, v[20:21], off nt
	global_load_dword v41, v[22:23], off nt
	global_load_dword v42, v[24:25], off nt
	global_load_dword v43, v[26:27], off nt
	global_load_dword v44, v[28:29], off nt
	v_or_b32_e32 v14, 32, v1
	v_or_b32_e32 v16, 34, v1
	v_or_b32_e32 v18, 36, v1
	v_or_b32_e32 v20, 38, v1
	v_or_b32_e32 v22, 40, v1
	v_or_b32_e32 v24, 42, v1
	v_or_b32_e32 v26, 44, v1
	v_mad_u64_u32 v[14:15], s[44:45], v14, s34, 0
	v_mad_u64_u32 v[16:17], s[44:45], v16, s34, 0
	v_mad_u64_u32 v[18:19], s[44:45], v18, s34, 0
	v_mad_u64_u32 v[20:21], s[44:45], v20, s34, 0
	v_mad_u64_u32 v[22:23], s[44:45], v22, s34, 0
	v_mad_u64_u32 v[24:25], s[44:45], v24, s34, 0
	v_mad_u64_u32 v[26:27], s[44:45], v26, s34, 0
	v_or_b32_e32 v28, 46, v1
	v_add_u32_e32 v15, s37, v15
	v_add_u32_e32 v17, s37, v17
	v_add_u32_e32 v19, s37, v19
	v_add_u32_e32 v21, s37, v21
	v_add_u32_e32 v23, s37, v23
	v_add_u32_e32 v25, s37, v25
	v_add_u32_e32 v27, s37, v27
	v_mad_u64_u32 v[28:29], s[44:45], v28, s34, 0
	v_lshl_add_u64 v[14:15], v[14:15], 2, v[12:13]
	v_lshl_add_u64 v[16:17], v[16:17], 2, v[12:13]
	v_lshl_add_u64 v[18:19], v[18:19], 2, v[12:13]
	v_lshl_add_u64 v[20:21], v[20:21], 2, v[12:13]
	v_lshl_add_u64 v[22:23], v[22:23], 2, v[12:13]
	v_lshl_add_u64 v[24:25], v[24:25], 2, v[12:13]
	v_lshl_add_u64 v[26:27], v[26:27], 2, v[12:13]
	v_add_u32_e32 v29, s37, v29
	v_lshl_add_u64 v[28:29], v[28:29], 2, v[12:13]
	global_load_dword v45, v[14:15], off nt
	global_load_dword v46, v[16:17], off nt
	global_load_dword v47, v[18:19], off nt
	global_load_dword v48, v[20:21], off nt
	global_load_dword v49, v[22:23], off nt
	global_load_dword v50, v[24:25], off nt
	global_load_dword v51, v[26:27], off nt
	global_load_dword v52, v[28:29], off nt
	v_or_b32_e32 v14, 48, v1
; #define LAS __attribute__((address_space(3)))
; __device__ __forceinline__ unsigned pk2(float lo, float hi) { return f2bf(lo) | (f2bf(hi) << 16); }
; __device__ __forceinline__ void transpose_item(const float* W, int K, int N, bf16_t* WT, LAS float* scr, int item, int lane) {
;     ...
;     for (int i = 0; i < 32; ++i) wv[i] = W[(size_t)(k0 + 2 * i + (lane >> 5)) * N + n0 + (lane & 31)];
; #pragma unroll
;     for (int i = 0; i < 32; ++i) scr[(2 * i + (lane >> 5)) * 33 + (lane & 31)] = wv[i];
;     asm volatile("s_waitcnt lgkmcnt(0)" ::: "memory");
;     const int c = lane & 7;
; #pragma unroll
;     for (int j = 0; j < 4; ++j) { const int n = (lane >> 3) + 8 * j; const LAS float* s = scr + (8 * c) * 33 + n;
;         u32x4 o; o.x = pk2(s[0 * 33], s[1 * 33]); o.y = pk2(s[2 * 33], s[3 * 33]); o.z = pk2(s[4 * 33], s[5 * 33]); o.w = pk2(s[6 * 33], s[7 * 33]);
;         *(u32x4*)(WT + (size_t)(n0 + n) * K + k0 + 8 * c) = o; }
	v_or_b32_e32 v16, 50, v1
	v_or_b32_e32 v18, 52, v1
	v_or_b32_e32 v20, 54, v1
	v_or_b32_e32 v22, 56, v1
	v_or_b32_e32 v24, 58, v1
	v_or_b32_e32 v26, 60, v1
	v_or_b32_e32 v1, 62, v1
	v_mad_u64_u32 v[14:15], s[44:45], v14, s34, 0
	v_mad_u64_u32 v[16:17], s[44:45], v16, s34, 0
	v_mad_u64_u32 v[18:19], s[44:45], v18, s34, 0
	v_mad_u64_u32 v[20:21], s[44:45], v20, s34, 0
	v_mad_u64_u32 v[22:23], s[44:45], v22, s34, 0
	v_mad_u64_u32 v[24:25], s[44:45], v24, s34, 0
	v_mad_u64_u32 v[26:27], s[44:45], v26, s34, 0
	v_mad_u64_u32 v[28:29], s[44:45], v1, s34, 0
	v_add_u32_e32 v15, s37, v15
	v_add_u32_e32 v17, s37, v17
	v_add_u32_e32 v19, s37, v19
	v_add_u32_e32 v21, s37, v21
	v_add_u32_e32 v23, s37, v23
	v_add_u32_e32 v25, s37, v25
	v_add_u32_e32 v27, s37, v27
	v_add_u32_e32 v29, s37, v29
	v_lshl_add_u64 v[14:15], v[14:15], 2, v[12:13]
	v_lshl_add_u64 v[16:17], v[16:17], 2, v[12:13]
	v_lshl_add_u64 v[18:19], v[18:19], 2, v[12:13]
	v_lshl_add_u64 v[20:21], v[20:21], 2, v[12:13]
	v_lshl_add_u64 v[22:23], v[22:23], 2, v[12:13]
	v_lshl_add_u64 v[24:25], v[24:25], 2, v[12:13]
	v_lshl_add_u64 v[26:27], v[26:27], 2, v[12:13]
	v_lshl_add_u64 v[12:13], v[28:29], 2, v[12:13]
	global_load_dword v1, v[14:15], off nt
	s_nop 0
	global_load_dword v14, v[16:17], off nt
	global_load_dword v15, v[18:19], off nt
	s_nop 0
	global_load_dword v16, v[20:21], off nt
	global_load_dword v17, v[22:23], off nt
	global_load_dword v18, v[24:25], off nt
	global_load_dword v19, v[26:27], off nt
	s_nop 0
	global_load_dword v12, v[12:13], off nt
	s_waitcnt vmcnt(30)
	ds_write2_b32 v10, v11, v30 offset1:66
	s_waitcnt vmcnt(28)
	ds_write2_b32 v10, v31, v32 offset0:132 offset1:198
	v_add_u32_e32 v11, 0x400, v10
	s_waitcnt vmcnt(26)
	ds_write2_b32 v11, v33, v34 offset0:8 offset1:74
	s_waitcnt vmcnt(24)
	ds_write2_b32 v11, v35, v36 offset0:140 offset1:206
	v_add_u32_e32 v11, 0x800, v10
	s_waitcnt vmcnt(22)
	ds_write2_b32 v11, v37, v38 offset0:16 offset1:82
	s_waitcnt vmcnt(20)
	ds_write2_b32 v11, v39, v40 offset0:148 offset1:214
	v_add_u32_e32 v11, 0xc00, v10
	s_waitcnt vmcnt(18)
	ds_write2_b32 v11, v41, v42 offset0:24 offset1:90
	s_waitcnt vmcnt(16)
	ds_write2_b32 v11, v43, v44 offset0:156 offset1:222
	v_add_u32_e32 v11, 0x1000, v10
	s_waitcnt vmcnt(14)
	ds_write2_b32 v11, v45, v46 offset0:32 offset1:98
	s_waitcnt vmcnt(12)
	ds_write2_b32 v11, v47, v48 offset0:164 offset1:230
	v_add_u32_e32 v11, 0x1400, v10
	s_waitcnt vmcnt(10)
	ds_write2_b32 v11, v49, v50 offset0:40 offset1:106
	s_waitcnt vmcnt(8)
	ds_write2_b32 v11, v51, v52 offset0:172 offset1:238
	v_add_u32_e32 v11, 0x1800, v10
	s_waitcnt vmcnt(6)
	ds_write2_b32 v11, v1, v14 offset0:48 offset1:114
	s_waitcnt vmcnt(4)
	ds_write2_b32 v11, v15, v16 offset0:180 offset1:246
	v_add_u32_e32 v1, 0x1c00, v10
	s_waitcnt vmcnt(2)
	ds_write2_b32 v1, v17, v18 offset0:56 offset1:122
	s_waitcnt vmcnt(0)
	ds_write2_b32 v1, v19, v12 offset0:188 offset1:254
	s_waitcnt lgkmcnt(0)
	ds_read2_b32 v[16:17], v6 offset1:8
	ds_read2_b32 v[20:21], v6 offset0:33 offset1:41
	s_lshl_b64 s[44:45], s[72:73], 1
	s_add_u32 s44, s60, s44
	ds_read2_b32 v[22:23], v6 offset0:66 offset1:74
	s_addc_u32 s45, s61, s45
	v_mov_b32_e32 v1, v97
	ds_read2_b32 v[24:25], v6 offset0:99 offset1:107
	v_lshl_add_u64 v[18:19], s[44:45], 0, v[0:1]
	s_waitcnt lgkmcnt(3)
	v_bfe_u32 v1, v16, 16, 1
	v_add3_u32 v1, v16, v1, s28
	s_waitcnt lgkmcnt(2)
	v_bfe_u32 v11, v20, 16, 1
	ds_read2_b32 v[26:27], v6 offset0:132 offset1:140
	v_lshrrev_b32_e32 v1, 16, v1
	v_add3_u32 v11, v20, v11, s28
	ds_read2_b32 v[28:29], v6 offset0:165 offset1:173
	v_and_or_b32 v12, v11, s39, v1
	s_waitcnt lgkmcnt(3)
	v_bfe_u32 v1, v22, 16, 1
	v_add3_u32 v1, v22, v1, s28
	s_waitcnt lgkmcnt(2)
	v_bfe_u32 v11, v24, 16, 1
	ds_read2_b32 v[30:31], v6 offset0:198 offset1:206
	v_lshrrev_b32_e32 v1, 16, v1
	v_add3_u32 v11, v24, v11, s28
	ds_read2_b32 v[32:33], v6 offset0:231 offset1:239
	v_and_or_b32 v13, v11, s39, v1
	s_waitcnt lgkmcnt(3)
	v_bfe_u32 v1, v26, 16, 1
	v_add3_u32 v1, v26, v1, s28
	s_waitcnt lgkmcnt(2)
; #define LAS __attribute__((address_space(3)))
; __device__ __forceinline__ unsigned pk2(float lo, float hi) { return f2bf(lo) | (f2bf(hi) << 16); }
; __device__ __forceinline__ void transpose_item(const float* W, int K, int N, bf16_t* WT, LAS float* scr, int item, int lane) {
;     ...
;     const int c = lane & 7;
; #pragma unroll
;     for (int j = 0; j < 4; ++j) { const int n = (lane >> 3) + 8 * j; const LAS float* s = scr + (8 * c) * 33 + n;
;         u32x4 o; o.x = pk2(s[0 * 33], s[1 * 33]); o.y = pk2(s[2 * 33], s[3 * 33]); o.z = pk2(s[4 * 33], s[5 * 33]); o.w = pk2(s[6 * 33], s[7 * 33]);
;         *(u32x4*)(WT + (size_t)(n0 + n) * K + k0 + 8 * c) = o; }
;     asm volatile("s_waitcnt lgkmcnt(0)" ::: "memory");
	v_bfe_u32 v11, v28, 16, 1
	v_lshrrev_b32_e32 v1, 16, v1
	v_add3_u32 v11, v28, v11, s28
	v_and_or_b32 v14, v11, s39, v1
	s_waitcnt lgkmcnt(1)
	v_bfe_u32 v1, v30, 16, 1
	v_add3_u32 v1, v30, v1, s28
	s_waitcnt lgkmcnt(0)
	v_bfe_u32 v11, v32, 16, 1
	v_lshrrev_b32_e32 v1, 16, v1
	v_add3_u32 v11, v32, v11, s28
	v_and_or_b32 v15, v11, s39, v1
	v_or_b32_e32 v1, s22, v5
	v_mul_lo_u32 v11, s59, v1
	v_mad_u64_u32 v[34:35], s[44:45], s58, v1, 0
	s_mul_i32 s34, s58, s23
	v_bfe_u32 v1, v17, 16, 1
	v_add3_u32 v35, v35, s34, v11
	v_add3_u32 v1, v17, v1, s28
	v_bfe_u32 v11, v21, 16, 1
	v_lshl_add_u64 v[34:35], v[34:35], 1, v[18:19]
	v_lshrrev_b32_e32 v1, 16, v1
	v_add3_u32 v11, v21, v11, s28
	global_store_dwordx4 v[34:35], v[12:15], off
	ds_read2_b32 v[20:21], v6 offset0:16 offset1:24
	s_add_i32 s36, s36, s26
	v_and_or_b32 v12, v11, s39, v1
	v_bfe_u32 v1, v23, 16, 1
	v_add3_u32 v1, v23, v1, s28
	v_bfe_u32 v11, v25, 16, 1
	v_lshrrev_b32_e32 v1, 16, v1
	v_add3_u32 v11, v25, v11, s28
	v_and_or_b32 v13, v11, s39, v1
	v_bfe_u32 v1, v27, 16, 1
	v_add3_u32 v1, v27, v1, s28
	v_bfe_u32 v11, v29, 16, 1
	v_lshrrev_b32_e32 v1, 16, v1
	v_add3_u32 v11, v29, v11, s28
	v_and_or_b32 v14, v11, s39, v1
	v_bfe_u32 v1, v31, 16, 1
	v_add3_u32 v1, v31, v1, s28
	v_bfe_u32 v11, v33, 16, 1
	v_lshrrev_b32_e32 v1, 16, v1
	v_add3_u32 v11, v33, v11, s28
	v_and_or_b32 v15, v11, s39, v1
	v_or_b32_e32 v1, s22, v7
	v_mul_lo_u32 v11, s59, v1
	v_mad_u64_u32 v[16:17], s[44:45], s58, v1, 0
	v_add3_u32 v17, v17, s34, v11
	v_lshl_add_u64 v[16:17], v[16:17], 1, v[18:19]
	global_store_dwordx4 v[16:17], v[12:15], off
	ds_read2_b32 v[16:17], v6 offset0:49 offset1:57
	ds_read2_b32 v[22:23], v6 offset0:82 offset1:90
	ds_read2_b32 v[24:25], v6 offset0:115 offset1:123
	s_waitcnt lgkmcnt(3)
	v_bfe_u32 v1, v20, 16, 1
	v_add3_u32 v1, v20, v1, s28
	s_waitcnt lgkmcnt(2)
	v_bfe_u32 v11, v16, 16, 1
	ds_read2_b32 v[26:27], v6 offset0:148 offset1:156
	v_lshrrev_b32_e32 v1, 16, v1
	v_add3_u32 v11, v16, v11, s28
	ds_read2_b32 v[28:29], v6 offset0:181 offset1:189
	v_and_or_b32 v12, v11, s39, v1
	s_waitcnt lgkmcnt(3)
	v_bfe_u32 v1, v22, 16, 1
	v_add3_u32 v1, v22, v1, s28
	s_waitcnt lgkmcnt(2)
	v_bfe_u32 v11, v24, 16, 1
	ds_read2_b32 v[30:31], v6 offset0:214 offset1:222
	v_lshrrev_b32_e32 v1, 16, v1
	v_add3_u32 v11, v24, v11, s28
	ds_read2_b32 v[32:33], v6 offset0:247 offset1:255
	v_and_or_b32 v13, v11, s39, v1
	s_waitcnt lgkmcnt(3)
	v_bfe_u32 v1, v26, 16, 1
	v_add3_u32 v1, v26, v1, s28
	s_waitcnt lgkmcnt(2)
	v_bfe_u32 v11, v28, 16, 1
	v_lshrrev_b32_e32 v1, 16, v1
	v_add3_u32 v11, v28, v11, s28
	v_and_or_b32 v14, v11, s39, v1
	s_waitcnt lgkmcnt(1)
	v_bfe_u32 v1, v30, 16, 1
	v_add3_u32 v1, v30, v1, s28
	s_waitcnt lgkmcnt(0)
	v_bfe_u32 v11, v32, 16, 1
	v_lshrrev_b32_e32 v1, 16, v1
	v_add3_u32 v11, v32, v11, s28
	v_and_or_b32 v15, v11, s39, v1
	v_or_b32_e32 v1, s22, v8
	v_mul_lo_u32 v11, s59, v1
	v_mad_u64_u32 v[34:35], s[44:45], s58, v1, 0
	v_bfe_u32 v1, v21, 16, 1
	v_add3_u32 v35, v35, s34, v11
	v_add3_u32 v1, v21, v1, s28
	v_bfe_u32 v11, v17, 16, 1
	v_lshl_add_u64 v[34:35], v[34:35], 1, v[18:19]
	v_lshrrev_b32_e32 v1, 16, v1
	v_add3_u32 v11, v17, v11, s28
	global_store_dwordx4 v[34:35], v[12:15], off
	s_cmpk_lt_i32 s36, 0x1880
	s_nop 0
	v_and_or_b32 v12, v11, s39, v1
	v_bfe_u32 v1, v23, 16, 1
	v_add3_u32 v1, v23, v1, s28
	v_bfe_u32 v11, v25, 16, 1
	v_lshrrev_b32_e32 v1, 16, v1
	v_add3_u32 v11, v25, v11, s28
	v_and_or_b32 v13, v11, s39, v1
	v_bfe_u32 v1, v27, 16, 1
	v_add3_u32 v1, v27, v1, s28
	v_bfe_u32 v11, v29, 16, 1
	v_lshrrev_b32_e32 v1, 16, v1
	v_add3_u32 v11, v29, v11, s28
	v_and_or_b32 v14, v11, s39, v1
	v_bfe_u32 v1, v31, 16, 1
	v_add3_u32 v1, v31, v1, s28
	v_bfe_u32 v11, v33, 16, 1
	v_lshrrev_b32_e32 v1, 16, v1
	v_add3_u32 v11, v33, v11, s28
	v_and_or_b32 v15, v11, s39, v1
	v_or_b32_e32 v1, s22, v9
	v_mul_lo_u32 v11, s59, v1
	v_mad_u64_u32 v[16:17], s[22:23], s58, v1, 0
	v_add3_u32 v17, v17, s34, v11
	v_lshl_add_u64 v[16:17], v[16:17], 1, v[18:19]
	global_store_dwordx4 v[16:17], v[12:15], off
	s_waitcnt lgkmcnt(0)
	s_cbranch_scc0 .LBB0_1208

; #define LAS __attribute__((address_space(3)))
; __device__ __forceinline__ void transpose_item(const float* W, int K, int N, bf16_t* WT, LAS float* scr, int item, int lane) {
;     const int nblk = N / 32, kb = item / nblk, nb = item % nblk, k0 = 64 * kb, n0 = 32 * nb;
;     float wv[32];
; #pragma unroll
;     for (int i = 0; i < 32; ++i) wv[i] = W[(size_t)(k0 + 2 * i + (lane >> 5)) * N + n0 + (lane & 31)];
; #pragma unroll
;     for (int i = 0; i < 32; ++i) scr[(2 * i + (lane >> 5)) * 33 + (lane & 31)] = wv[i];
.LBB0_1221:
	s_lshr_b32 s22, s34, 5
	v_cvt_f32_u32_e32 v1, s22
	s_sub_i32 s78, 0, s22
	s_abs_i32 s74, s75
	s_ashr_i32 s23, s75, 31
	v_rcp_iflag_f32_e32 v1, v1
	s_nop 0
	v_mul_f32_e32 v1, 0x4f7ffffe, v1
	v_cvt_u32_f32_e32 v1, v1
	s_nop 0
	v_readfirstlane_b32 s79, v1
	s_mul_i32 s78, s78, s79
	s_mul_hi_u32 s78, s79, s78
	s_add_i32 s79, s79, s78
	s_mul_hi_u32 s78, s74, s79
	s_mul_i32 s79, s78, s22
	s_sub_i32 s74, s74, s79
	s_add_i32 s80, s78, 1
	s_sub_i32 s79, s74, s22
	s_cmp_ge_u32 s74, s22
	s_cselect_b32 s78, s80, s78
	s_cselect_b32 s74, s79, s74
	s_add_i32 s79, s78, 1
	s_cmp_ge_u32 s74, s22
	s_cselect_b32 s74, s79, s78
	s_xor_b32 s74, s74, s23
	s_sub_i32 s23, s74, s23
	s_mul_i32 s22, s23, s22
	s_sub_i32 s22, s75, s22
	s_lshl_b32 s22, s22, 5
	s_lshl_b32 s74, s23, 6
	s_ashr_i32 s23, s22, 31
	s_lshl_b64 s[78:79], s[22:23], 2
	v_or_b32_e32 v1, s74, v2
	s_add_u32 s72, s72, s78
	s_addc_u32 s73, s73, s79
	s_ashr_i32 s75, s74, 31
	v_or_b32_e32 v14, 2, v1
	v_or_b32_e32 v16, 4, v1
	v_or_b32_e32 v18, 6, v1
	v_or_b32_e32 v20, 8, v1
	v_or_b32_e32 v22, 10, v1
	v_or_b32_e32 v24, 12, v1
	v_lshl_add_u64 v[10:11], s[72:73], 0, v[96:97]
	s_mul_i32 s72, s75, s34
	v_mad_u64_u32 v[12:13], s[78:79], v1, s34, 0
	v_mad_u64_u32 v[14:15], s[78:79], v14, s34, 0
	v_mad_u64_u32 v[16:17], s[78:79], v16, s34, 0
	v_mad_u64_u32 v[18:19], s[78:79], v18, s34, 0
	v_mad_u64_u32 v[20:21], s[78:79], v20, s34, 0
	v_mad_u64_u32 v[22:23], s[78:79], v22, s34, 0
	v_mad_u64_u32 v[24:25], s[78:79], v24, s34, 0
	v_or_b32_e32 v26, 14, v1
	v_add_u32_e32 v13, s72, v13
	v_add_u32_e32 v15, s72, v15
	v_add_u32_e32 v17, s72, v17
	v_add_u32_e32 v19, s72, v19
	v_add_u32_e32 v21, s72, v21
	v_add_u32_e32 v23, s72, v23
	v_add_u32_e32 v25, s72, v25
	v_mad_u64_u32 v[26:27], s[78:79], v26, s34, 0
	v_lshl_add_u64 v[12:13], v[12:13], 2, v[10:11]
	v_lshl_add_u64 v[14:15], v[14:15], 2, v[10:11]
	v_lshl_add_u64 v[16:17], v[16:17], 2, v[10:11]
	v_lshl_add_u64 v[18:19], v[18:19], 2, v[10:11]
	v_lshl_add_u64 v[20:21], v[20:21], 2, v[10:11]
	v_lshl_add_u64 v[22:23], v[22:23], 2, v[10:11]
	v_lshl_add_u64 v[24:25], v[24:25], 2, v[10:11]
	v_add_u32_e32 v27, s72, v27
	v_lshl_add_u64 v[26:27], v[26:27], 2, v[10:11]
	global_load_dword v28, v[12:13], off nt
	global_load_dword v29, v[14:15], off nt
	global_load_dword v30, v[16:17], off nt
	global_load_dword v31, v[18:19], off nt
	global_load_dword v32, v[20:21], off nt
	global_load_dword v33, v[22:23], off nt
	global_load_dword v34, v[24:25], off nt
	global_load_dword v35, v[26:27], off nt
	v_or_b32_e32 v12, 16, v1
	v_or_b32_e32 v14, 18, v1
	v_or_b32_e32 v16, 20, v1
	v_or_b32_e32 v18, 22, v1
	v_or_b32_e32 v20, 24, v1
	v_or_b32_e32 v22, 26, v1
	v_or_b32_e32 v24, 28, v1
	v_mad_u64_u32 v[12:13], s[78:79], v12, s34, 0
	v_mad_u64_u32 v[14:15], s[78:79], v14, s34, 0
	v_mad_u64_u32 v[16:17], s[78:79], v16, s34, 0
	v_mad_u64_u32 v[18:19], s[78:79], v18, s34, 0
	v_mad_u64_u32 v[20:21], s[78:79], v20, s34, 0
	v_mad_u64_u32 v[22:23], s[78:79], v22, s34, 0
	v_mad_u64_u32 v[24:25], s[78:79], v24, s34, 0
	v_or_b32_e32 v26, 30, v1
	v_add_u32_e32 v13, s72, v13
	v_add_u32_e32 v15, s72, v15
	v_add_u32_e32 v17, s72, v17
	v_add_u32_e32 v19, s72, v19
	v_add_u32_e32 v21, s72, v21
	v_add_u32_e32 v23, s72, v23
	v_add_u32_e32 v25, s72, v25
	v_mad_u64_u32 v[26:27], s[78:79], v26, s34, 0
	v_lshl_add_u64 v[12:13], v[12:13], 2, v[10:11]
	v_lshl_add_u64 v[14:15], v[14:15], 2, v[10:11]
	v_lshl_add_u64 v[16:17], v[16:17], 2, v[10:11]
	v_lshl_add_u64 v[18:19], v[18:19], 2, v[10:11]
	v_lshl_add_u64 v[20:21], v[20:21], 2, v[10:11]
	v_lshl_add_u64 v[22:23], v[22:23], 2, v[10:11]
	v_lshl_add_u64 v[24:25], v[24:25], 2, v[10:11]
	v_add_u32_e32 v27, s72, v27
	v_lshl_add_u64 v[26:27], v[26:27], 2, v[10:11]
	global_load_dword v36, v[12:13], off nt
	global_load_dword v37, v[14:15], off nt
	global_load_dword v38, v[16:17], off nt
	global_load_dword v39, v[18:19], off nt
	global_load_dword v40, v[20:21], off nt
	global_load_dword v41, v[22:23], off nt
	global_load_dword v42, v[24:25], off nt
	global_load_dword v43, v[26:27], off nt
	v_or_b32_e32 v12, 32, v1
	v_or_b32_e32 v14, 34, v1
	v_or_b32_e32 v16, 36, v1
	v_or_b32_e32 v18, 38, v1
	v_or_b32_e32 v20, 40, v1
	v_or_b32_e32 v22, 42, v1
	v_or_b32_e32 v24, 44, v1
	v_mad_u64_u32 v[12:13], s[78:79], v12, s34, 0
	v_mad_u64_u32 v[14:15], s[78:79], v14, s34, 0
	v_mad_u64_u32 v[16:17], s[78:79], v16, s34, 0
	v_mad_u64_u32 v[18:19], s[78:79], v18, s34, 0
	v_mad_u64_u32 v[20:21], s[78:79], v20, s34, 0
	v_mad_u64_u32 v[22:23], s[78:79], v22, s34, 0
	v_mad_u64_u32 v[24:25], s[78:79], v24, s34, 0
	v_or_b32_e32 v26, 46, v1
	v_add_u32_e32 v13, s72, v13
	v_add_u32_e32 v15, s72, v15
	v_add_u32_e32 v17, s72, v17
	v_add_u32_e32 v19, s72, v19
	v_add_u32_e32 v21, s72, v21
	v_add_u32_e32 v23, s72, v23
	v_add_u32_e32 v25, s72, v25
	v_mad_u64_u32 v[26:27], s[78:79], v26, s34, 0
	v_lshl_add_u64 v[12:13], v[12:13], 2, v[10:11]
	v_lshl_add_u64 v[14:15], v[14:15], 2, v[10:11]
	v_lshl_add_u64 v[16:17], v[16:17], 2, v[10:11]
	v_lshl_add_u64 v[18:19], v[18:19], 2, v[10:11]
	v_lshl_add_u64 v[20:21], v[20:21], 2, v[10:11]
	v_lshl_add_u64 v[22:23], v[22:23], 2, v[10:11]
	v_lshl_add_u64 v[24:25], v[24:25], 2, v[10:11]
	v_add_u32_e32 v27, s72, v27
	v_lshl_add_u64 v[26:27], v[26:27], 2, v[10:11]
	global_load_dword v44, v[12:13], off nt
	global_load_dword v45, v[14:15], off nt
	global_load_dword v46, v[16:17], off nt
	global_load_dword v47, v[18:19], off nt
	global_load_dword v48, v[20:21], off nt
	global_load_dword v49, v[22:23], off nt
	global_load_dword v50, v[24:25], off nt
	global_load_dword v51, v[26:27], off nt
	v_or_b32_e32 v12, 48, v1
	v_or_b32_e32 v14, 50, v1
	v_or_b32_e32 v16, 52, v1
; #define LAS __attribute__((address_space(3)))
; __device__ __forceinline__ unsigned pk2(float lo, float hi) { return f2bf(lo) | (f2bf(hi) << 16); }
; __device__ __forceinline__ void transpose_item(const float* W, int K, int N, bf16_t* WT, LAS float* scr, int item, int lane) {
;     ...
;     for (int i = 0; i < 32; ++i) wv[i] = W[(size_t)(k0 + 2 * i + (lane >> 5)) * N + n0 + (lane & 31)];
; #pragma unroll
;     for (int i = 0; i < 32; ++i) scr[(2 * i + (lane >> 5)) * 33 + (lane & 31)] = wv[i];
;     asm volatile("s_waitcnt lgkmcnt(0)" ::: "memory");
;     const int c = lane & 7;
; #pragma unroll
;     for (int j = 0; j < 4; ++j) { const int n = (lane >> 3) + 8 * j; const LAS float* s = scr + (8 * c) * 33 + n;
;         u32x4 o; o.x = pk2(s[0 * 33], s[1 * 33]); o.y = pk2(s[2 * 33], s[3 * 33]); o.z = pk2(s[4 * 33], s[5 * 33]); o.w = pk2(s[6 * 33], s[7 * 33]);
;         *(u32x4*)(WT + (size_t)(n0 + n) * K + k0 + 8 * c) = o; }
	v_or_b32_e32 v18, 54, v1
	v_or_b32_e32 v20, 56, v1
	v_or_b32_e32 v22, 58, v1
	v_or_b32_e32 v24, 60, v1
	v_or_b32_e32 v1, 62, v1
	v_mad_u64_u32 v[12:13], s[78:79], v12, s34, 0
	v_mad_u64_u32 v[14:15], s[78:79], v14, s34, 0
	v_mad_u64_u32 v[16:17], s[78:79], v16, s34, 0
	v_mad_u64_u32 v[18:19], s[78:79], v18, s34, 0
	v_mad_u64_u32 v[20:21], s[78:79], v20, s34, 0
	v_mad_u64_u32 v[22:23], s[78:79], v22, s34, 0
	v_mad_u64_u32 v[24:25], s[78:79], v24, s34, 0
	v_mad_u64_u32 v[26:27], s[78:79], v1, s34, 0
	v_add_u32_e32 v13, s72, v13
	v_add_u32_e32 v15, s72, v15
	v_add_u32_e32 v17, s72, v17
	v_add_u32_e32 v19, s72, v19
	v_add_u32_e32 v21, s72, v21
	v_add_u32_e32 v23, s72, v23
	v_add_u32_e32 v25, s72, v25
	v_add_u32_e32 v27, s72, v27
	v_lshl_add_u64 v[12:13], v[12:13], 2, v[10:11]
	v_lshl_add_u64 v[14:15], v[14:15], 2, v[10:11]
	v_lshl_add_u64 v[16:17], v[16:17], 2, v[10:11]
	v_lshl_add_u64 v[18:19], v[18:19], 2, v[10:11]
	v_lshl_add_u64 v[20:21], v[20:21], 2, v[10:11]
	v_lshl_add_u64 v[22:23], v[22:23], 2, v[10:11]
	v_lshl_add_u64 v[24:25], v[24:25], 2, v[10:11]
	v_lshl_add_u64 v[10:11], v[26:27], 2, v[10:11]
	global_load_dword v1, v[12:13], off nt
	s_nop 0
	global_load_dword v12, v[14:15], off nt
	global_load_dword v13, v[16:17], off nt
	s_nop 0
	global_load_dword v14, v[18:19], off nt
	global_load_dword v15, v[20:21], off nt
	global_load_dword v16, v[22:23], off nt
	global_load_dword v17, v[24:25], off nt
	s_nop 0
	global_load_dword v10, v[10:11], off nt
	v_add_u32_e32 v11, 0x400, v9
	s_waitcnt vmcnt(0)
	ds_write2_b32 v9, v28, v29 offset1:66
	ds_write2_b32 v9, v30, v31 offset0:132 offset1:198
	ds_write2_b32 v11, v32, v33 offset0:8 offset1:74
	ds_write2_b32 v11, v34, v35 offset0:140 offset1:206
	v_add_u32_e32 v11, 0x800, v9
	ds_write2_b32 v11, v36, v37 offset0:16 offset1:82
	ds_write2_b32 v11, v38, v39 offset0:148 offset1:214
	v_add_u32_e32 v11, 0xc00, v9
	ds_write2_b32 v11, v40, v41 offset0:24 offset1:90
	ds_write2_b32 v11, v42, v43 offset0:156 offset1:222
	v_add_u32_e32 v11, 0x1000, v9
	ds_write2_b32 v11, v44, v45 offset0:32 offset1:98
	ds_write2_b32 v11, v46, v47 offset0:164 offset1:230
	v_add_u32_e32 v11, 0x1400, v9
	ds_write2_b32 v11, v48, v49 offset0:40 offset1:106
	ds_write2_b32 v11, v50, v51 offset0:172 offset1:238
	v_add_u32_e32 v11, 0x1800, v9
	ds_write2_b32 v11, v1, v12 offset0:48 offset1:114
	ds_write2_b32 v11, v13, v14 offset0:180 offset1:246
	v_add_u32_e32 v1, 0x1c00, v9
	ds_write2_b32 v1, v15, v16 offset0:56 offset1:122
	ds_write2_b32 v1, v17, v10 offset0:188 offset1:254
	s_waitcnt lgkmcnt(0)
	ds_read2_b32 v[14:15], v5 offset1:8
	ds_read2_b32 v[18:19], v5 offset0:33 offset1:41
	s_lshl_b64 s[72:73], s[74:75], 1
	s_add_u32 s70, s70, s72
	ds_read2_b32 v[20:21], v5 offset0:66 offset1:74
	s_addc_u32 s71, s71, s73
	v_mov_b32_e32 v1, v97
	ds_read2_b32 v[22:23], v5 offset0:99 offset1:107
	v_lshl_add_u64 v[16:17], s[70:71], 0, v[0:1]
	s_waitcnt lgkmcnt(0)
	v_bfe_u32 v1, v14, 16, 1
	v_add3_u32 v1, v14, v1, s28
	v_bfe_u32 v10, v18, 16, 1
	ds_read2_b32 v[24:25], v5 offset0:132 offset1:140
	v_lshrrev_b32_e32 v1, 16, v1
	v_add3_u32 v10, v18, v10, s28
	ds_read2_b32 v[26:27], v5 offset0:165 offset1:173
	v_and_or_b32 v10, v10, s39, v1
	v_bfe_u32 v1, v20, 16, 1
	v_add3_u32 v1, v20, v1, s28
	v_bfe_u32 v11, v22, 16, 1
	ds_read2_b32 v[28:29], v5 offset0:198 offset1:206
	v_lshrrev_b32_e32 v1, 16, v1
	v_add3_u32 v11, v22, v11, s28
	ds_read2_b32 v[30:31], v5 offset0:231 offset1:239
	v_and_or_b32 v11, v11, s39, v1
	s_waitcnt lgkmcnt(3)
	v_bfe_u32 v1, v24, 16, 1
	v_add3_u32 v1, v24, v1, s28
	s_waitcnt lgkmcnt(2)
	v_bfe_u32 v12, v26, 16, 1
	v_lshrrev_b32_e32 v1, 16, v1
	v_add3_u32 v12, v26, v12, s28
	v_and_or_b32 v12, v12, s39, v1
	s_waitcnt lgkmcnt(1)
	v_bfe_u32 v1, v28, 16, 1
	v_add3_u32 v1, v28, v1, s28
	s_waitcnt lgkmcnt(0)
; #define LAS __attribute__((address_space(3)))
; __device__ __forceinline__ unsigned pk2(float lo, float hi) { return f2bf(lo) | (f2bf(hi) << 16); }
; __device__ __forceinline__ void transpose_item(const float* W, int K, int N, bf16_t* WT, LAS float* scr, int item, int lane) {
;     ...
;     const int c = lane & 7;
; #pragma unroll
;     for (int j = 0; j < 4; ++j) { const int n = (lane >> 3) + 8 * j; const LAS float* s = scr + (8 * c) * 33 + n;
;         u32x4 o; o.x = pk2(s[0 * 33], s[1 * 33]); o.y = pk2(s[2 * 33], s[3 * 33]); o.z = pk2(s[4 * 33], s[5 * 33]); o.w = pk2(s[6 * 33], s[7 * 33]);
;         *(u32x4*)(WT + (size_t)(n0 + n) * K + k0 + 8 * c) = o; }
;     asm volatile("s_waitcnt lgkmcnt(0)" ::: "memory");
	v_bfe_u32 v13, v30, 16, 1
	v_lshrrev_b32_e32 v1, 16, v1
	v_add3_u32 v13, v30, v13, s28
	v_and_or_b32 v13, v13, s39, v1
	v_or_b32_e32 v1, s22, v3
	v_mul_lo_u32 v14, s61, v1
	v_mad_u64_u32 v[32:33], s[70:71], s60, v1, 0
	s_mul_i32 s34, s60, s23
	v_add3_u32 v33, v33, s34, v14
	v_lshl_add_u64 v[32:33], v[32:33], 1, v[16:17]
	v_bfe_u32 v1, v15, 16, 1
	global_store_dwordx4 v[32:33], v[10:13], off
	v_add3_u32 v1, v15, v1, s28
	v_lshrrev_b32_e32 v1, 16, v1
	v_bfe_u32 v10, v19, 16, 1
	v_add3_u32 v10, v19, v10, s28
	v_and_or_b32 v10, v10, s39, v1
	v_bfe_u32 v1, v21, 16, 1
	v_add3_u32 v1, v21, v1, s28
	v_bfe_u32 v11, v23, 16, 1
	v_lshrrev_b32_e32 v1, 16, v1
	v_add3_u32 v11, v23, v11, s28
	v_and_or_b32 v11, v11, s39, v1
	v_bfe_u32 v1, v25, 16, 1
	v_add3_u32 v1, v25, v1, s28
	v_bfe_u32 v12, v27, 16, 1
	v_lshrrev_b32_e32 v1, 16, v1
	v_add3_u32 v12, v27, v12, s28
	v_and_or_b32 v12, v12, s39, v1
	v_bfe_u32 v1, v29, 16, 1
	v_add3_u32 v1, v29, v1, s28
	v_bfe_u32 v13, v31, 16, 1
	v_lshrrev_b32_e32 v1, 16, v1
	v_add3_u32 v13, v31, v13, s28
	v_and_or_b32 v13, v13, s39, v1
	v_or_b32_e32 v1, s22, v6
	v_mul_lo_u32 v20, s61, v1
	v_mad_u64_u32 v[14:15], s[70:71], s60, v1, 0
	v_add3_u32 v15, v15, s34, v20
	ds_read2_b32 v[18:19], v5 offset0:16 offset1:24
	v_lshl_add_u64 v[14:15], v[14:15], 1, v[16:17]
	global_store_dwordx4 v[14:15], v[10:13], off
	ds_read2_b32 v[14:15], v5 offset0:49 offset1:57
	ds_read2_b32 v[20:21], v5 offset0:82 offset1:90
	ds_read2_b32 v[22:23], v5 offset0:115 offset1:123
	s_waitcnt lgkmcnt(3)
	v_bfe_u32 v1, v18, 16, 1
	v_add3_u32 v1, v18, v1, s28
	s_waitcnt lgkmcnt(2)
	v_bfe_u32 v10, v14, 16, 1
	ds_read2_b32 v[24:25], v5 offset0:148 offset1:156
	v_lshrrev_b32_e32 v1, 16, v1
	v_add3_u32 v10, v14, v10, s28
	ds_read2_b32 v[26:27], v5 offset0:181 offset1:189
	v_and_or_b32 v10, v10, s39, v1
	s_waitcnt lgkmcnt(3)
	v_bfe_u32 v1, v20, 16, 1
	v_add3_u32 v1, v20, v1, s28
	s_waitcnt lgkmcnt(2)
	v_bfe_u32 v11, v22, 16, 1
	ds_read2_b32 v[28:29], v5 offset0:214 offset1:222
	v_lshrrev_b32_e32 v1, 16, v1
	v_add3_u32 v11, v22, v11, s28
	ds_read2_b32 v[30:31], v5 offset0:247 offset1:255
	v_and_or_b32 v11, v11, s39, v1
	s_waitcnt lgkmcnt(3)
	v_bfe_u32 v1, v24, 16, 1
	v_add3_u32 v1, v24, v1, s28
	s_waitcnt lgkmcnt(2)
	v_bfe_u32 v12, v26, 16, 1
	v_lshrrev_b32_e32 v1, 16, v1
	v_add3_u32 v12, v26, v12, s28
	v_and_or_b32 v12, v12, s39, v1
	s_waitcnt lgkmcnt(1)
	v_bfe_u32 v1, v28, 16, 1
	v_add3_u32 v1, v28, v1, s28
	s_waitcnt lgkmcnt(0)
	v_bfe_u32 v13, v30, 16, 1
	v_lshrrev_b32_e32 v1, 16, v1
	v_add3_u32 v13, v30, v13, s28
	v_and_or_b32 v13, v13, s39, v1
	v_or_b32_e32 v1, s22, v7
	v_mul_lo_u32 v14, s61, v1
	v_mad_u64_u32 v[32:33], s[70:71], s60, v1, 0
	v_add3_u32 v33, v33, s34, v14
	v_lshl_add_u64 v[32:33], v[32:33], 1, v[16:17]
	v_bfe_u32 v1, v19, 16, 1
	global_store_dwordx4 v[32:33], v[10:13], off
	v_add3_u32 v1, v19, v1, s28
	v_lshrrev_b32_e32 v1, 16, v1
	v_bfe_u32 v10, v15, 16, 1
	v_add3_u32 v10, v15, v10, s28
	v_and_or_b32 v10, v10, s39, v1
	v_bfe_u32 v1, v21, 16, 1
	v_add3_u32 v1, v21, v1, s28
	v_bfe_u32 v11, v23, 16, 1
	v_lshrrev_b32_e32 v1, 16, v1
	v_add3_u32 v11, v23, v11, s28
	v_and_or_b32 v11, v11, s39, v1
	v_bfe_u32 v1, v25, 16, 1
	v_add3_u32 v1, v25, v1, s28
	v_bfe_u32 v12, v27, 16, 1
	v_lshrrev_b32_e32 v1, 16, v1
	v_add3_u32 v12, v27, v12, s28
	v_and_or_b32 v12, v12, s39, v1
	v_bfe_u32 v1, v29, 16, 1
	v_add3_u32 v1, v29, v1, s28
	v_bfe_u32 v13, v31, 16, 1
	v_lshrrev_b32_e32 v1, 16, v1
	v_add3_u32 v13, v31, v13, s28
	v_and_or_b32 v13, v13, s39, v1
	v_or_b32_e32 v1, s22, v8
	v_mul_lo_u32 v18, s61, v1
	v_mad_u64_u32 v[14:15], s[22:23], s60, v1, 0
	v_add3_u32 v15, v15, s34, v18
	v_lshl_add_u64 v[14:15], v[14:15], 1, v[16:17]
	global_store_dwordx4 v[14:15], v[10:13], off
	s_add_i32 s76, s76, s26
	s_waitcnt lgkmcnt(0)
	s_add_i32 s77, s77, s26
	s_add_i32 s64, s64, s26
	s_add_i32 s69, s69, s26
	s_add_i32 s68, s68, s26
	s_add_i32 s65, s65, s26
	s_add_i32 s22, s89, s76
	s_cmp_lt_i32 s22, s49
	s_cbranch_scc0 .LBB0_1210
